# LDS fragment reads spread across PV MFMA gaps; QK waits split
# baseline (speedup 1.0000x reference)
; DI void diff_core(unsigned char* smem, const u16* qptr, const u16* kbase, const u16* vtbase, int vld,
;                   int ntb, int ntw, int nvalid, int ks0, const float* lut, int qpos, bool active, bool grpB,
;                   f32x16 (&O)[4], float& l_out) {
;     ...
;   auto qk = [&](int slot) {
;     if (grpB) __builtin_amdgcn_s_setprio(2); else __builtin_amdgcn_s_setprio(1);
;     const float ini = -m;
; #pragma unroll
;     for (int kb = 0; kb < 2; ++kb)
; #pragma unroll
;       for (int e = 0; e < 16; ++e) S[kb][e] = ini;
;     const LAS unsigned char* b = lds + slot * D_SLOT;
;     bf16x8 kf[4][2];
; #pragma unroll
;     ...
;   auto pv = [&](int slot) {
;     if (grpB) __builtin_amdgcn_s_setprio(2); else __builtin_amdgcn_s_setprio(1);
;     const LAS unsigned char* b = lds + slot * D_SLOT;
;     bf16x8 va[4], vb[4];
; #pragma unroll
;     for (int tt = 0; tt < 4; ++tt) va[tt] = *reinterpret_cast<const LAS bf16x8*>(b + voff[0] + tt * 32 * 128);
; #pragma unroll
;     for (int tt = 0; tt < 4; ++tt) vb[tt] = *reinterpret_cast<const LAS bf16x8*>(b + voff[1] + tt * 32 * 128);
;     {
;       const bf16x8 pf = __builtin_bit_cast(bf16x8, P[0]);
; #pragma unroll
;       for (int tt = 0; tt < 4; ++tt) O[tt] = MFMA(va[tt], pf, O[tt]);
;     }
; #pragma unroll
;     for (int tt = 0; tt < 4; ++tt) va[tt] = *reinterpret_cast<const LAS bf16x8*>(b + voff[2] + tt * 32 * 128);
;     {
;       const bf16x8 pf = __builtin_bit_cast(bf16x8, P[1]);
; #pragma unroll
;       for (int tt = 0; tt < 4; ++tt) O[tt] = MFMA(vb[tt], pf, O[tt]);
;     }
; #pragma unroll
;     for (int tt = 0; tt < 4; ++tt) vb[tt] = *reinterpret_cast<const LAS bf16x8*>(b + voff[3] + tt * 32 * 128);
;     {
;       const bf16x8 pf = __builtin_bit_cast(bf16x8, P[2]);
; #pragma unroll
;       for (int tt = 0; tt < 4; ++tt) O[tt] = MFMA(va[tt], pf, O[tt]);
;     }
;     {
;       const bf16x8 pf = __builtin_bit_cast(bf16x8, P[3]);
; #pragma unroll
;       for (int tt = 0; tt < 4; ++tt) O[tt] = MFMA(vb[tt], pf, O[tt]);
;     }
;     __builtin_amdgcn_sched_group_barrier(0x100, 8, 0);
;     __builtin_amdgcn_sched_group_barrier(0x008, 4, 0);
;     __builtin_amdgcn_sched_group_barrier(0x100, 4, 0);
;     __builtin_amdgcn_sched_group_barrier(0x008, 4, 0);
;     __builtin_amdgcn_sched_group_barrier(0x100, 4, 0);
;     __builtin_amdgcn_sched_group_barrier(0x008, 8, 0);
;     __builtin_amdgcn_s_setprio(0);
;   };
.LBB0_360:
	s_add_i32 s66, s64, 0x101
	s_cmp_gt_u32 s66, s16
	s_cbranch_scc1 .LBB0_362
	s_setprio 2
	s_and_b32 s0, s65, 0x18000
	v_add_u32_e32 v248, s0, v197
	ds_read_b128 v[64:67], v248 offset:16384
	ds_read_b128 v[68:71], v248 offset:20480
	ds_read_b128 v[72:75], v248 offset:24576
	ds_read_b128 v[76:79], v248 offset:28672
	s_add_i32 s67, s65, 0xfffe8000
	s_and_b32 s67, s67, 0x18000
	v_cvt_pk_bf16_f32 v144, v96, v97
	v_cvt_pk_bf16_f32 v145, v98, v99
	v_cvt_pk_bf16_f32 v146, v100, v101
	v_cvt_pk_bf16_f32 v147, v102, v103
	v_add_f32_e32 v250, v97, v96
	v_add_f32_e32 v250, v98, v250
	s_waitcnt lgkmcnt(4)
	v_mfma_f32_32x32x16_bf16 v[48:63], v[200:203], v[144:147], v[48:63]
	v_cvt_pk_bf16_f32 v148, v104, v105
	v_add_f32_e32 v250, v99, v250
	v_add_f32_e32 v250, v100, v250
	v_add_u32_e32 v249, s0, v198
	ds_read_b128 v[80:83], v249 offset:16384
	v_mfma_f32_32x32x16_bf16 v[32:47], v[204:207], v[144:147], v[32:47]
	v_cvt_pk_bf16_f32 v149, v106, v107
	v_add_f32_e32 v250, v101, v250
	v_add_f32_e32 v250, v102, v250
	ds_read_b128 v[84:87], v249 offset:20480
	v_mfma_f32_32x32x16_bf16 v[16:31], v[208:211], v[144:147], v[16:31]
	v_cvt_pk_bf16_f32 v150, v108, v109
	v_add_f32_e32 v250, v103, v250
	v_add_f32_e32 v250, v104, v250
	ds_read_b128 v[88:91], v249 offset:24576
	v_mfma_f32_32x32x16_bf16 v[0:15], v[212:215], v[144:147], v[0:15]
	v_cvt_pk_bf16_f32 v151, v110, v111
	v_add_f32_e32 v250, v105, v250
	v_add_f32_e32 v250, v106, v250
	ds_read_b128 v[92:95], v249 offset:28672
	v_mfma_f32_32x32x16_bf16 v[48:63], v[216:219], v[148:151], v[48:63]
	v_cvt_pk_bf16_f32 v152, v112, v113
	v_add_f32_e32 v250, v107, v250
	v_add_f32_e32 v250, v108, v250
	v_add_u32_e32 v248, s67, v177
	ds_read_b128 v[200:203], v248
	v_mfma_f32_32x32x16_bf16 v[32:47], v[220:223], v[148:151], v[32:47]
	v_cvt_pk_bf16_f32 v153, v114, v115
	v_add_f32_e32 v250, v109, v250
	v_add_f32_e32 v250, v110, v250
	ds_read_b128 v[204:207], v248 offset:8192
	v_mfma_f32_32x32x16_bf16 v[16:31], v[224:227], v[148:151], v[16:31]
	v_cvt_pk_bf16_f32 v154, v116, v117
	v_add_f32_e32 v250, v111, v250
	v_add_f32_e32 v250, v112, v250
	v_add_u32_e32 v249, s67, v178
	ds_read_b128 v[208:211], v249
	v_mfma_f32_32x32x16_bf16 v[0:15], v[228:231], v[148:151], v[0:15]
	v_cvt_pk_bf16_f32 v155, v118, v119
	v_add_f32_e32 v250, v113, v250
	v_add_f32_e32 v250, v114, v250
	ds_read_b128 v[212:215], v249 offset:8192
	s_waitcnt lgkmcnt(8)
	v_mfma_f32_32x32x16_bf16 v[48:63], v[64:67], v[152:155], v[48:63]
	v_cvt_pk_bf16_f32 v156, v120, v121
	v_add_f32_e32 v250, v115, v250
	v_add_f32_e32 v250, v116, v250
	v_add_u32_e32 v248, s67, v179
	ds_read_b128 v[216:219], v248
	v_mfma_f32_32x32x16_bf16 v[32:47], v[68:71], v[152:155], v[32:47]
	v_cvt_pk_bf16_f32 v157, v122, v123
	v_add_f32_e32 v250, v117, v250
	v_add_f32_e32 v250, v118, v250
	ds_read_b128 v[220:223], v248 offset:8192
	v_mfma_f32_32x32x16_bf16 v[16:31], v[72:75], v[152:155], v[16:31]
	v_cvt_pk_bf16_f32 v158, v124, v125
	v_add_f32_e32 v250, v119, v250
	v_add_f32_e32 v250, v120, v250
	v_add_u32_e32 v249, s67, v180
	ds_read_b128 v[224:227], v249
	v_mfma_f32_32x32x16_bf16 v[0:15], v[76:79], v[152:155], v[0:15]
	v_cvt_pk_bf16_f32 v159, v126, v127
	v_add_f32_e32 v250, v121, v250
	v_add_f32_e32 v250, v122, v250
	ds_read_b128 v[228:231], v249 offset:8192
	s_waitcnt lgkmcnt(8)
	v_mfma_f32_32x32x16_bf16 v[48:63], v[80:83], v[156:159], v[48:63]
	v_add_f32_e32 v250, v123, v250
	v_add_f32_e32 v250, v124, v250
	v_mfma_f32_32x32x16_bf16 v[32:47], v[84:87], v[156:159], v[32:47]
	v_add_f32_e32 v250, v125, v250
	v_add_f32_e32 v250, v126, v250
	v_mfma_f32_32x32x16_bf16 v[16:31], v[88:91], v[156:159], v[16:31]
	v_add_f32_e32 v250, v127, v250
	v_mfma_f32_32x32x16_bf16 v[0:15], v[92:95], v[156:159], v[0:15]
	v_add_f32_e32 v181, v181, v250
	s_setprio 0
.LBB0_362:
	s_cmp_lt_u32 s66, s16
	s_cselect_b64 s[0:1], -1, 0
	s_cmp_ge_u32 s66, s16
	s_cbranch_scc1 .LBB0_364
	s_setprio 2
	s_waitcnt lgkmcnt(4)
	v_mfma_f32_32x32x16_bf16 v[96:111], v[200:203], v[128:131], v[232:247]
	v_mfma_f32_32x32x16_bf16 v[112:127], v[204:207], v[128:131], v[232:247]
	v_mfma_f32_32x32x16_bf16 v[96:111], v[208:211], v[132:135], v[96:111]
	v_mfma_f32_32x32x16_bf16 v[112:127], v[212:215], v[132:135], v[112:127]
	s_waitcnt lgkmcnt(0)
	v_mfma_f32_32x32x16_bf16 v[96:111], v[216:219], v[136:139], v[96:111]
	v_mfma_f32_32x32x16_bf16 v[112:127], v[220:223], v[136:139], v[112:127]
	v_mfma_f32_32x32x16_bf16 v[96:111], v[224:227], v[140:143], v[96:111]
	v_mfma_f32_32x32x16_bf16 v[112:127], v[228:231], v[140:143], v[112:127]
	s_setprio 0

; DI void diff_core(unsigned char* smem, const u16* qptr, const u16* kbase, const u16* vtbase, int vld,
;                   int ntb, int ntw, int nvalid, int ks0, const float* lut, int qpos, bool active, bool grpB,
;                   f32x16 (&O)[4], float& l_out) {
;     ...
;   auto qk = [&](int slot) {
;     if (grpB) __builtin_amdgcn_s_setprio(2); else __builtin_amdgcn_s_setprio(1);
;     const float ini = -m;
; #pragma unroll
;     for (int kb = 0; kb < 2; ++kb)
; #pragma unroll
;       for (int e = 0; e < 16; ++e) S[kb][e] = ini;
;     const LAS unsigned char* b = lds + slot * D_SLOT;
;     bf16x8 kf[4][2];
; #pragma unroll
;     ...
;   auto pv = [&](int slot) {
;     if (grpB) __builtin_amdgcn_s_setprio(2); else __builtin_amdgcn_s_setprio(1);
;     const LAS unsigned char* b = lds + slot * D_SLOT;
;     bf16x8 va[4], vb[4];
; #pragma unroll
;     for (int tt = 0; tt < 4; ++tt) va[tt] = *reinterpret_cast<const LAS bf16x8*>(b + voff[0] + tt * 32 * 128);
; #pragma unroll
;     for (int tt = 0; tt < 4; ++tt) vb[tt] = *reinterpret_cast<const LAS bf16x8*>(b + voff[1] + tt * 32 * 128);
;     {
;       const bf16x8 pf = __builtin_bit_cast(bf16x8, P[0]);
; #pragma unroll
;       for (int tt = 0; tt < 4; ++tt) O[tt] = MFMA(va[tt], pf, O[tt]);
;     }
; #pragma unroll
;     for (int tt = 0; tt < 4; ++tt) va[tt] = *reinterpret_cast<const LAS bf16x8*>(b + voff[2] + tt * 32 * 128);
;     {
;       const bf16x8 pf = __builtin_bit_cast(bf16x8, P[1]);
; #pragma unroll
;       for (int tt = 0; tt < 4; ++tt) O[tt] = MFMA(vb[tt], pf, O[tt]);
;     }
; #pragma unroll
;     for (int tt = 0; tt < 4; ++tt) vb[tt] = *reinterpret_cast<const LAS bf16x8*>(b + voff[3] + tt * 32 * 128);
;     {
;       const bf16x8 pf = __builtin_bit_cast(bf16x8, P[2]);
; #pragma unroll
;       for (int tt = 0; tt < 4; ++tt) O[tt] = MFMA(va[tt], pf, O[tt]);
;     }
;     {
;       const bf16x8 pf = __builtin_bit_cast(bf16x8, P[3]);
; #pragma unroll
;       for (int tt = 0; tt < 4; ++tt) O[tt] = MFMA(vb[tt], pf, O[tt]);
;     }
;     __builtin_amdgcn_sched_group_barrier(0x100, 8, 0);
;     __builtin_amdgcn_sched_group_barrier(0x008, 4, 0);
;     __builtin_amdgcn_sched_group_barrier(0x100, 4, 0);
;     __builtin_amdgcn_sched_group_barrier(0x008, 4, 0);
;     __builtin_amdgcn_sched_group_barrier(0x100, 4, 0);
;     __builtin_amdgcn_sched_group_barrier(0x008, 8, 0);
;     __builtin_amdgcn_s_setprio(0);
;   };
.LBB0_384:
	s_waitcnt vmcnt(4)
	s_barrier
	s_andn2_b64 vcc, exec, s[0:1]
	s_cbranch_vccnz .LBB0_386
	s_setprio 2
	s_waitcnt lgkmcnt(0)
	v_mfma_f32_32x32x16_bf16 v[48:63], v[200:203], v[144:147], v[48:63]
	v_cvt_pk_bf16_f32 v148, v88, v89
	v_add_f32_e32 v250, v83, v250
	v_add_f32_e32 v250, v84, v250
	v_add_u32_e32 v97, s100, v186
	ds_read_b128 v[98:101], v97 offset:16384
	v_mfma_f32_32x32x16_bf16 v[32:47], v[204:207], v[144:147], v[32:47]
	v_cvt_pk_bf16_f32 v149, v90, v91
	v_add_f32_e32 v250, v85, v250
	v_add_f32_e32 v250, v86, v250
	ds_read_b128 v[102:105], v97 offset:20480
	v_mfma_f32_32x32x16_bf16 v[16:31], v[208:211], v[144:147], v[16:31]
	v_cvt_pk_bf16_f32 v150, v92, v93
	v_add_f32_e32 v250, v87, v250
	v_add_f32_e32 v250, v88, v250
	ds_read_b128 v[106:109], v97 offset:24576
	v_mfma_f32_32x32x16_bf16 v[0:15], v[212:215], v[144:147], v[0:15]
	v_cvt_pk_bf16_f32 v151, v94, v95
	v_add_f32_e32 v250, v89, v250
	v_add_f32_e32 v250, v90, v250
	ds_read_b128 v[110:113], v97 offset:28672
	v_mfma_f32_32x32x16_bf16 v[48:63], v[216:219], v[148:151], v[48:63]
	v_cvt_pk_bf16_f32 v152, v64, v65
	v_add_f32_e32 v250, v91, v250
	v_add_f32_e32 v250, v92, v250
	v_add_u32_e32 v126, s100, v184
	ds_read_b128 v[114:117], v126 offset:16384
	v_add_u32_e32 v248, s101, v177
	ds_read_b128 v[200:203], v248
	v_mfma_f32_32x32x16_bf16 v[32:47], v[220:223], v[148:151], v[32:47]
	v_cvt_pk_bf16_f32 v153, v66, v67
	v_add_f32_e32 v250, v93, v250
	v_add_f32_e32 v250, v94, v250
	ds_read_b128 v[118:121], v126 offset:20480
	ds_read_b128 v[204:207], v248 offset:8192
	v_mfma_f32_32x32x16_bf16 v[16:31], v[224:227], v[148:151], v[16:31]
	v_cvt_pk_bf16_f32 v154, v68, v69
	v_add_f32_e32 v250, v95, v250
	v_add_f32_e32 v250, v64, v250
	ds_read_b128 v[122:125], v126 offset:24576
	v_add_u32_e32 v249, s101, v178
	ds_read_b128 v[208:211], v249
	v_mfma_f32_32x32x16_bf16 v[0:15], v[228:231], v[148:151], v[0:15]
	v_cvt_pk_bf16_f32 v155, v70, v71
	v_add_f32_e32 v250, v65, v250
	v_add_f32_e32 v250, v66, v250
	ds_read_b128 v[196:199], v126 offset:28672
	ds_read_b128 v[212:215], v249 offset:8192
	s_waitcnt lgkmcnt(8)
	v_mfma_f32_32x32x16_bf16 v[48:63], v[98:101], v[152:155], v[48:63]
	v_cvt_pk_bf16_f32 v156, v72, v73
	v_add_f32_e32 v250, v67, v250
	v_add_f32_e32 v250, v68, v250
	v_add_u32_e32 v248, s101, v179
	ds_read_b128 v[216:219], v248
	v_mfma_f32_32x32x16_bf16 v[32:47], v[102:105], v[152:155], v[32:47]
	v_cvt_pk_bf16_f32 v157, v74, v75
	v_add_f32_e32 v250, v69, v250
	v_add_f32_e32 v250, v70, v250
	ds_read_b128 v[220:223], v248 offset:8192
	v_mfma_f32_32x32x16_bf16 v[16:31], v[106:109], v[152:155], v[16:31]
	v_cvt_pk_bf16_f32 v158, v76, v77
	v_add_f32_e32 v250, v71, v250
	v_add_f32_e32 v250, v72, v250
	v_add_u32_e32 v249, s101, v180
	ds_read_b128 v[224:227], v249
	v_mfma_f32_32x32x16_bf16 v[0:15], v[110:113], v[152:155], v[0:15]
	v_cvt_pk_bf16_f32 v159, v78, v79
	v_add_f32_e32 v250, v73, v250
	v_add_f32_e32 v250, v74, v250
	ds_read_b128 v[228:231], v249 offset:8192
	s_waitcnt lgkmcnt(5)
	v_mfma_f32_32x32x16_bf16 v[48:63], v[114:117], v[156:159], v[48:63]
	v_add_f32_e32 v250, v75, v250
	v_add_f32_e32 v250, v76, v250
	v_mfma_f32_32x32x16_bf16 v[32:47], v[118:121], v[156:159], v[32:47]
	v_add_f32_e32 v250, v77, v250
	v_add_f32_e32 v250, v78, v250
	v_mfma_f32_32x32x16_bf16 v[16:31], v[122:125], v[156:159], v[16:31]
	v_add_f32_e32 v250, v79, v250
	v_mfma_f32_32x32x16_bf16 v[0:15], v[196:199], v[156:159], v[0:15]
	v_add_f32_e32 v181, v181, v250
	s_setprio 0
.LBB0_386:
	s_add_i32 s0, s62, 0x102
	s_cmp_ge_u32 s0, s16
	s_cbranch_scc1 .LB_dma_only
	s_setprio 2
	s_waitcnt lgkmcnt(4)
	s_mov_b32 m0, s85
	v_mfma_f32_32x32x16_bf16 v[80:95], v[200:203], v[128:131], v[232:247]
	global_load_lds_dwordx4 v162, s[86:87]
	v_mfma_f32_32x32x16_bf16 v[64:79], v[204:207], v[128:131], v[232:247]
	s_mov_b32 m0, s65
	v_mfma_f32_32x32x16_bf16 v[80:95], v[208:211], v[132:135], v[80:95]
	global_load_lds_dwordx4 v170, s[86:87]
	v_mfma_f32_32x32x16_bf16 v[64:79], v[212:215], v[132:135], v[64:79]
	s_waitcnt lgkmcnt(0)
	s_mov_b32 m0, s88
	v_mfma_f32_32x32x16_bf16 v[80:95], v[216:219], v[136:139], v[80:95]
	global_load_lds_dwordx4 v166, s[66:67]
	v_mfma_f32_32x32x16_bf16 v[64:79], v[220:223], v[136:139], v[64:79]
	s_mov_b32 m0, s89
	v_mfma_f32_32x32x16_bf16 v[80:95], v[224:227], v[140:143], v[80:95]
	global_load_lds_dwordx4 v168, s[66:67]
	v_mfma_f32_32x32x16_bf16 v[64:79], v[228:231], v[140:143], v[64:79]
	s_setprio 0
	s_branch .LBB0_377
